# grid-barrier waiter spin loops back off with s_sleep 4 instead of 1 (master poll unchanged), on top of v040
# speedup vs baseline: 1.0072x; 1.0072x over previous
; __device__ __forceinline__ unsigned xb_ld(unsigned* p)              { return __hip_atomic_load(p, __ATOMIC_RELAXED, __HIP_MEMORY_SCOPE_AGENT); }
; #define XB_SPIN(cond, bar) do { unsigned _sp = 0; while (cond) { __builtin_amdgcn_s_sleep(1); \
;     if ((++_sp & 255u) == 0u) { if (xb_ld(&(bar)[XB_TMO])) break; if (_sp > XB_SPIN_CAP) { atomicAdd(&(bar)[XB_TMO], 1u); break; } } } } while (0)
; __device__ __forceinline__ void xcd_barrier(const XcdBarrier& b) {
;     ...
;             XB_SPIN(xb_ld(&bar[XB_XGEN(b.x)]) == gen, bar);
.LBB0_140:
	s_and_b32 s3, s2, 0xff
	s_mov_b64 s[42:43], -1
	s_cmp_lg_u32 s3, 0
	s_mov_b64 s[46:47], -1
	s_sleep 4
	s_cbranch_scc1 .LBB0_143
	global_load_dword v2, v0, s[12:13] sc1
	s_waitcnt vmcnt(0)
	v_cmp_eq_u32_e32 vcc, 0, v2
	s_cbranch_vccnz .LBB0_145
	s_mov_b64 s[46:47], 0
	s_mov_b64 s[44:45], -1

; __device__ __forceinline__ unsigned xb_ld(unsigned* p)              { return __hip_atomic_load(p, __ATOMIC_RELAXED, __HIP_MEMORY_SCOPE_AGENT); }
; #define XB_SPIN(cond, bar) do { unsigned _sp = 0; while (cond) { __builtin_amdgcn_s_sleep(1); \
;     if ((++_sp & 255u) == 0u) { if (xb_ld(&(bar)[XB_TMO])) break; if (_sp > XB_SPIN_CAP) { atomicAdd(&(bar)[XB_TMO], 1u); break; } } } } while (0)
; __device__ __forceinline__ void xcd_barrier(const XcdBarrier& b) {
;     ...
;             XB_SPIN(xb_ld(&bar[XB_XGEN(b.x)]) == gen, bar);
.LBB0_471:
	s_and_b32 s3, s2, 0xff
	s_mov_b64 s[46:47], -1
	s_cmp_lg_u32 s3, 0
	s_mov_b64 s[50:51], -1
	s_sleep 4
	s_cbranch_scc1 .LBB0_474
	global_load_dword v2, v0, s[12:13] sc1
	s_waitcnt vmcnt(0)
	v_cmp_eq_u32_e32 vcc, 0, v2
	s_cbranch_vccnz .LBB0_476
	s_mov_b64 s[50:51], 0
	s_mov_b64 s[48:49], -1

; __device__ __forceinline__ unsigned xb_ld(unsigned* p)              { return __hip_atomic_load(p, __ATOMIC_RELAXED, __HIP_MEMORY_SCOPE_AGENT); }
; #define XB_SPIN(cond, bar) do { unsigned _sp = 0; while (cond) { __builtin_amdgcn_s_sleep(1); \
;     if ((++_sp & 255u) == 0u) { if (xb_ld(&(bar)[XB_TMO])) break; if (_sp > XB_SPIN_CAP) { atomicAdd(&(bar)[XB_TMO], 1u); break; } } } } while (0)
; __device__ __forceinline__ void xcd_barrier(const XcdBarrier& b) {
;     ...
;             XB_SPIN(xb_ld(&bar[XB_XGEN(b.x)]) == gen, bar);
.LBB0_545:
	s_and_b32 s3, s2, 0xff
	s_mov_b64 s[44:45], -1
	s_cmp_lg_u32 s3, 0
	s_mov_b64 s[48:49], -1
	s_sleep 4
	s_cbranch_scc1 .LBB0_548
	global_load_dword v2, v0, s[12:13] sc1
	s_waitcnt vmcnt(0)
	v_cmp_eq_u32_e32 vcc, 0, v2
	s_cbranch_vccnz .LBB0_550
	s_mov_b64 s[48:49], 0
	s_mov_b64 s[46:47], -1
